# attention loops: K tile restage (LDS stores) issued right after the PV segment instead of just before the barrier (its LDS-store latency off the barrier's critical path)
# speedup vs baseline: 1.0006x; 1.0006x over previous
.Lmskip_fox_1:
	s_waitcnt vmcnt(1)
	ds_write_b128 v193, v[154:157] offset:32768
	s_waitcnt vmcnt(0)
	ds_write_b128 v193, v[158:161] offset:40960
	s_sub_i32 s0, s11, s27
	s_cmp_ge_i32 s0, 95
	s_cbranch_scc1 .Lp1skip_fox_1
	ds_read_b128 v[66:69], v198
	ds_read_b128 v[70:73], v198 offset:32
	ds_read_b128 v[202:205], v198 offset:128
	ds_read_b128 v[206:209], v198 offset:160
	ds_read_b128 v[76:79], v198 offset:64
	ds_read_b128 v[210:213], v198 offset:96
	ds_read_b128 v[214:217], v198 offset:192
	ds_read_b128 v[220:223], v198 offset:224
	s_waitcnt lgkmcnt(7)
	s_waitcnt lgkmcnt(3)
	v_xor_b32_e32 v225, 0x80000000, v79
	v_xor_b32_e32 v224, 0x80000000, v78
	s_waitcnt lgkmcnt(2)
	v_fma_f32 v74, v110, s12, -v210
	v_fma_f32 v75, v111, s12, -v211
	v_fma_f32 v78, v106, s12, -v76
	v_fma_f32 v79, v107, s12, -v77
	v_fma_f32 v102, v102, s12, -v70
	v_fma_f32 v103, v103, s12, -v71
	v_fma_f32 v106, v108, s12, v224
	v_fma_f32 v107, v109, s12, v225
	v_xor_b32_e32 v109, 0x80000000, v205
	v_xor_b32_e32 v108, 0x80000000, v204
	v_xor_b32_e32 v111, 0x80000000, v209
	v_xor_b32_e32 v110, 0x80000000, v208
	s_waitcnt lgkmcnt(1)
	s_waitcnt lgkmcnt(0)
	v_fma_f32 v80, v112, s12, -v212
	v_fma_f32 v81, v113, s12, -v213
	v_fma_f32 v104, v104, s12, -v72
	v_fma_f32 v105, v105, s12, -v73
	v_fma_f32 v100, v100, s12, -v68
	v_fma_f32 v101, v101, s12, -v69
	v_fma_f32 v98, v98, s12, -v66
	v_fma_f32 v99, v99, s12, -v67
	v_fma_f32 v66, v94, s12, -v220
	v_fma_f32 v67, v95, s12, -v221
	v_fma_f32 v68, v90, s12, -v214
	v_fma_f32 v69, v91, s12, -v215
	v_fma_f32 v72, v86, s12, -v206
	v_fma_f32 v73, v87, s12, -v207
	v_fma_f32 v70, v96, s12, -v222
	v_fma_f32 v71, v97, s12, -v223
	v_fma_f32 v76, v92, s12, -v216
	v_fma_f32 v77, v93, s12, -v217
	v_fma_f32 v86, v88, s12, v110
	v_fma_f32 v87, v89, s12, v111
	v_fma_f32 v84, v84, s12, v108
	v_fma_f32 v85, v85, s12, v109
	s_cmp_le_i32 s11, s27
	v_fma_f32 v82, v82, s12, -v202
	v_fma_f32 v83, v83, s12, -v203
	s_cbranch_scc1 .LBB0_647
	v_add_u32_e32 v1, 64, v199
	v_cmp_gt_i32_e64 s[92:93], 26, v1
	v_cmp_gt_i32_e64 s[94:95], 27, v1
	v_cmp_gt_i32_e64 s[90:91], 25, v1
	s_and_b64 s[92:93], s[94:95], s[92:93]
	v_cmp_gt_i32_e64 s[88:89], 24, v1
	s_and_b64 s[90:91], s[92:93], s[90:91]
	v_cmp_gt_i32_e64 s[86:87], 19, v1
	s_and_b64 s[88:89], s[90:91], s[88:89]
	v_cmp_gt_i32_e64 s[84:85], 18, v1
	s_and_b64 s[86:87], s[88:89], s[86:87]
	v_cmp_gt_i32_e64 s[82:83], 17, v1
	s_and_b64 s[84:85], s[86:87], s[84:85]
	v_cmp_gt_i32_e64 s[80:81], 16, v1
	s_and_b64 s[82:83], s[84:85], s[82:83]
	v_cmp_gt_i32_e64 s[78:79], 11, v1
	s_and_b64 s[80:81], s[82:83], s[80:81]
	v_cmp_gt_i32_e64 s[76:77], 10, v1
	s_and_b64 s[78:79], s[80:81], s[78:79]
	v_cmp_gt_i32_e64 s[74:75], 9, v1
	s_and_b64 s[76:77], s[78:79], s[76:77]
	v_cmp_gt_i32_e64 s[72:73], 8, v1
	s_and_b64 s[74:75], s[76:77], s[74:75]
	v_cmp_gt_i32_e64 s[70:71], 3, v1
	s_and_b64 s[72:73], s[74:75], s[72:73]
	v_cmp_gt_i32_e64 s[68:69], 2, v1
	s_and_b64 s[70:71], s[72:73], s[70:71]
	v_cmp_gt_i32_e64 s[2:3], 1, v1
	s_and_b64 s[68:69], s[70:71], s[68:69]
	v_cmp_gt_i32_e64 s[0:1], 0, v1
	s_and_b64 s[2:3], s[68:69], s[2:3]
	s_and_b64 s[0:1], s[2:3], s[0:1]
	v_cmp_gt_i32_e64 s[66:67], 58, v1
	v_cndmask_b32_e64 v98, v98, v175, s[0:1]
	v_cmp_gt_i32_e64 s[0:1], 59, v1
	v_cmp_gt_i32_e64 s[64:65], 57, v1
	v_cmp_gt_i32_e64 s[62:63], 56, v1
	v_cndmask_b32_e64 v71, v71, v175, s[0:1]
	s_and_b64 s[0:1], s[0:1], s[66:67]
	v_cndmask_b32_e64 v70, v70, v175, s[0:1]
	s_and_b64 s[0:1], s[0:1], s[64:65]
	v_cmp_gt_i32_e64 s[60:61], 51, v1
	v_cndmask_b32_e64 v67, v67, v175, s[0:1]
	s_and_b64 s[0:1], s[0:1], s[62:63]
	v_cmp_gt_i32_e64 s[58:59], 50, v1
	v_cndmask_b32_e64 v66, v66, v175, s[0:1]
	s_and_b64 s[0:1], s[0:1], s[60:61]
	v_cmp_gt_i32_e64 s[56:57], 49, v1
	v_cndmask_b32_e64 v77, v77, v175, s[0:1]
	s_and_b64 s[0:1], s[0:1], s[58:59]
	v_cmp_gt_i32_e64 s[54:55], 48, v1
	v_cndmask_b32_e64 v76, v76, v175, s[0:1]
	s_and_b64 s[0:1], s[0:1], s[56:57]
	v_cmp_gt_i32_e64 s[52:53], 43, v1
	v_cndmask_b32_e64 v69, v69, v175, s[0:1]
	s_and_b64 s[0:1], s[0:1], s[54:55]
	v_cmp_gt_i32_e64 s[50:51], 42, v1
	v_cndmask_b32_e64 v68, v68, v175, s[0:1]
	s_and_b64 s[0:1], s[0:1], s[52:53]
	v_cmp_gt_i32_e64 s[48:49], 41, v1
	v_cndmask_b32_e64 v87, v87, v175, s[0:1]
	s_and_b64 s[0:1], s[0:1], s[50:51]
	v_cmp_gt_i32_e64 s[46:47], 40, v1
	v_cndmask_b32_e64 v86, v86, v175, s[0:1]
	s_and_b64 s[0:1], s[0:1], s[48:49]
	v_cmp_gt_i32_e64 s[44:45], 35, v1
	v_cndmask_b32_e64 v73, v73, v175, s[0:1]
	s_and_b64 s[0:1], s[0:1], s[46:47]
	v_cmp_gt_i32_e64 s[42:43], 34, v1
	v_cndmask_b32_e64 v72, v72, v175, s[0:1]
	s_and_b64 s[0:1], s[0:1], s[44:45]
	v_cmp_gt_i32_e64 s[40:41], 33, v1
	v_cndmask_b32_e64 v85, v85, v175, s[0:1]
	s_and_b64 s[0:1], s[0:1], s[42:43]
	v_cmp_gt_i32_e32 vcc, 32, v1
	v_cndmask_b32_e64 v84, v84, v175, s[0:1]
	s_and_b64 s[0:1], s[0:1], s[40:41]
	v_cndmask_b32_e64 v74, v74, v175, s[88:89]
	v_readlane_b32 s88, v242, 2
	s_and_b64 vcc, s[0:1], vcc
	v_cndmask_b32_e64 v81, v81, v175, s[94:95]
	v_cndmask_b32_e64 v80, v80, v175, s[92:93]
	s_movk_i32 s93, 0x6018
	s_mov_b32 s92, 0xf800000
	v_cndmask_b32_e64 v75, v75, v175, s[90:91]
	s_mov_b64 s[90:91], s[16:17]
	v_readlane_b32 s89, v242, 3
	v_cndmask_b32_e64 v107, v107, v175, s[86:87]
	v_readlane_b32 s86, v242, 0
	v_cndmask_b32_e64 v106, v106, v175, s[84:85]
	v_cndmask_b32_e64 v79, v79, v175, s[82:83]
	s_movk_i32 s83, 0x6000
	v_cndmask_b32_e64 v78, v78, v175, s[80:81]
	v_cndmask_b32_e64 v105, v105, v175, s[78:79]
	v_cndmask_b32_e64 v104, v104, v175, s[76:77]
	v_cndmask_b32_e64 v103, v103, v175, s[74:75]
	v_cndmask_b32_e64 v102, v102, v175, s[72:73]
	v_cndmask_b32_e64 v101, v101, v175, s[70:71]
	v_cndmask_b32_e64 v100, v100, v175, s[68:69]
	v_cndmask_b32_e64 v99, v99, v175, s[2:3]
	s_mov_b32 s56, s30
	v_cndmask_b32_e64 v83, v83, v175, s[0:1]
	v_cndmask_b32_e32 v82, v82, v175, vcc
	v_readlane_b32 s87, v242, 1

.Lp1join_fox_1:
	v_cmp_gt_f32_e32 vcc, 1.0, v108
	s_waitcnt lgkmcnt(0)
	s_barrier
	ds_write_b128 v194, v[146:149]
	ds_write_b128 v195, v[150:153]
	s_cbranch_vccz .LBB0_651
	s_and_saveexec_b64 s[0:1], s[38:39]
	ds_write_b32 v185, v108 offset:128
	s_or_b64 exec, exec, s[0:1]
	s_waitcnt lgkmcnt(0)
	ds_read_b128 v[88:91], v184 offset:224
	ds_read_b128 v[92:95], v184 offset:192
	ds_read_b128 v[110:113], v184 offset:160
	ds_read_b128 v[202:205], v184 offset:128
	s_waitcnt lgkmcnt(3)
	v_mul_f32 v64, v64, v90
	v_mul_f32 v65, v65, v91
	s_waitcnt lgkmcnt(2)
	v_mul_f32 v60, v60, v94
	v_mul_f32 v61, v61, v95
	s_waitcnt lgkmcnt(1)
	v_mul_f32 v56, v56, v112
	v_mul_f32 v57, v57, v113
	s_waitcnt lgkmcnt(0)
	v_mul_f32 v52, v52, v204
	v_mul_f32 v53, v53, v205
	v_mul_f32 v62, v62, v88
	v_mul_f32 v63, v63, v89
	v_mul_f32 v58, v58, v92
	v_mul_f32 v59, v59, v93
	v_mul_f32 v54, v54, v110
	v_mul_f32 v55, v55, v111
	v_mul_f32 v50, v50, v202
	v_mul_f32 v51, v51, v203
	v_mul_f32 v48, v48, v90
	v_mul_f32 v49, v49, v91
	v_mul_f32 v44, v44, v94
	v_mul_f32 v45, v45, v95
	v_mul_f32 v40, v40, v112
	v_mul_f32 v41, v41, v113
	v_mul_f32 v36, v36, v204
	v_mul_f32 v37, v37, v205
	v_mul_f32 v46, v46, v88
	v_mul_f32 v47, v47, v89
	v_mul_f32 v42, v42, v92
	v_mul_f32 v43, v43, v93
	v_mul_f32 v38, v38, v110
	v_mul_f32 v39, v39, v111
	v_mul_f32 v34, v34, v202
	v_mul_f32 v35, v35, v203
	v_mul_f32 v32, v32, v90
	v_mul_f32 v33, v33, v91
	v_mul_f32 v28, v28, v94
	v_mul_f32 v29, v29, v95
	v_mul_f32 v24, v24, v112
	v_mul_f32 v25, v25, v113
	v_mul_f32 v20, v20, v204
	v_mul_f32 v21, v21, v205
	v_mul_f32 v30, v30, v88
	v_mul_f32 v31, v31, v89
	v_mul_f32 v26, v26, v92
	v_mul_f32 v27, v27, v93
	v_mul_f32 v22, v22, v110
	v_mul_f32 v23, v23, v111
	v_mul_f32 v18, v18, v202
	v_mul_f32 v19, v19, v203
	v_mul_f32 v16, v16, v90
	v_mul_f32 v17, v17, v91
	v_mul_f32 v12, v12, v94
	v_mul_f32 v13, v13, v95
	v_mul_f32 v8, v8, v112
	v_mul_f32 v9, v9, v113
	v_mul_f32 v4, v4, v204
	v_mul_f32 v5, v5, v205
	v_mul_f32 v14, v14, v88
	v_mul_f32 v15, v15, v89
	v_mul_f32 v10, v10, v92
	v_mul_f32 v11, v11, v93
	v_mul_f32 v6, v6, v110
	v_mul_f32 v7, v7, v111
	v_mul_f32 v2, v2, v202
	v_mul_f32 v3, v3, v203

.Lmskip_fox_2:
	s_waitcnt lgkmcnt(0)
	s_sub_i32 s0, s11, s27
	s_cmp_ge_i32 s0, 95
	s_cbranch_scc1 .Lfskip_fox_3
	v_exp_f32_e32 v222, v104
	v_add_f32_e32 v104, 0, v196
	v_add_f32_e32 v104, v203, v104
	v_add_f32_e32 v104, v112, v104
	v_add_f32_e32 v104, v202, v104
	v_add_f32_e32 v104, v110, v104
	v_add_f32_e32 v104, v113, v104
	v_add_f32_e32 v104, v109, v104
	v_add_f32_e32 v104, v111, v104
	v_add_f32_e32 v104, v103, v104
	v_add_f32_e32 v104, v107, v104
	v_add_f32_e32 v104, v101, v104
	v_add_f32_e32 v104, v106, v104
	v_add_f32_e32 v104, v99, v104
	v_exp_f32_e32 v223, v105
	v_add_f32_e32 v104, v102, v104
	v_exp_f32_e32 v208, v208
	v_add_f32_e32 v104, v98, v104
	v_exp_f32_e32 v209, v209
	v_add_f32_e32 v104, v100, v104
	v_exp_f32_e32 v210, v210
	v_add_f32_e32 v104, v222, v104
	v_exp_f32_e32 v211, v211
	v_add_f32_e32 v104, v223, v104
	v_exp_f32_e32 v212, v212
	v_add_f32_e32 v104, v208, v104
	v_exp_f32_e32 v213, v213
	v_add_f32_e32 v104, v209, v104
	v_exp_f32_e32 v214, v214
	v_add_f32_e32 v104, v210, v104
	v_exp_f32_e32 v215, v215
	v_add_f32_e32 v104, v211, v104
	v_exp_f32_e32 v216, v216
	v_add_f32_e32 v104, v212, v104
	v_exp_f32_e32 v217, v217
	v_add_f32_e32 v104, v213, v104
	v_exp_f32_e32 v218, v218
	v_add_f32_e32 v104, v214, v104
	v_exp_f32_e32 v219, v219
	v_add_f32_e32 v104, v215, v104
	v_exp_f32_e32 v220, v220
	v_add_f32_e32 v104, v216, v104
	v_exp_f32_e32 v221, v221
	v_add_f32_e32 v104, v217, v104
	v_add_f32_e32 v104, v218, v104
	v_add_f32_e32 v104, v219, v104
	v_add_f32_e32 v104, v220, v104
	v_add_f32_e32 v104, v221, v104
	v_mov_b32_e32 v105, v104
	v_cvt_pk_bf16_f32 v204, v196, v203
	v_cvt_pk_bf16_f32 v205, v112, v202
	v_cvt_pk_bf16_f32 v206, v110, v113
	v_cvt_pk_bf16_f32 v207, v109, v111
	v_cvt_pk_bf16_f32 v110, v103, v107
	v_cvt_pk_bf16_f32 v111, v101, v106
	v_cvt_pk_bf16_f32 v112, v99, v102
	v_cvt_pk_bf16_f32 v113, v98, v100
	v_cvt_pk_bf16_f32 v98, v222, v223
	v_cvt_pk_bf16_f32 v99, v208, v209
	v_cvt_pk_bf16_f32 v100, v210, v211
	v_cvt_pk_bf16_f32 v101, v212, v213
	s_nop 1
	v_permlane32_swap_b32_e32 v104, v105
	v_permlane32_swap_b32_e32 v98, v100
	v_permlane32_swap_b32_e32 v99, v101
	v_cvt_pk_bf16_f32 v208, v214, v215
	v_cvt_pk_bf16_f32 v209, v216, v217
	v_cvt_pk_bf16_f32 v210, v218, v219
	v_cvt_pk_bf16_f32 v211, v220, v221
	v_permlane32_swap_b32_e32 v204, v206
	v_permlane32_swap_b32_e32 v205, v207
	v_permlane32_swap_b32_e32 v110, v112
	v_permlane32_swap_b32_e32 v111, v113
	v_permlane32_swap_b32_e32 v208, v210
	v_permlane32_swap_b32_e32 v209, v211
	ds_read_b64_tr_b16 v[212:213], v183 offset:0x4000
	ds_read_b64_tr_b16 v[214:215], v183 offset:0x4800
	ds_read_b64_tr_b16 v[216:217], v183 offset:0x5000
	ds_read_b64_tr_b16 v[218:219], v183 offset:0x5800
	ds_read_b64_tr_b16 v[220:221], v183 offset:0x6000
	ds_read_b64_tr_b16 v[222:223], v183 offset:0x6800
	ds_read_b64_tr_b16 v[224:225], v183 offset:0x7000
	ds_read_b64_tr_b16 v[226:227], v183 offset:0x7800
	s_nop 0
	s_waitcnt lgkmcnt(6)
	v_mfma_f32_32x32x16_bf16 v[50:65], v[204:207], v[212:215], v[50:65]
	ds_read_b64_tr_b16 v[212:213], v183 offset:0x4200
	ds_read_b64_tr_b16 v[214:215], v183 offset:0x4a00
	s_waitcnt lgkmcnt(6)
	v_mfma_f32_32x32x16_bf16 v[50:65], v[110:113], v[216:219], v[50:65]
	ds_read_b64_tr_b16 v[216:217], v183 offset:0x5200
	ds_read_b64_tr_b16 v[218:219], v183 offset:0x5a00
	s_waitcnt lgkmcnt(6)
	v_mfma_f32_32x32x16_bf16 v[50:65], v[98:101], v[220:223], v[50:65]
	ds_read_b64_tr_b16 v[220:221], v183 offset:0x6200
	ds_read_b64_tr_b16 v[222:223], v183 offset:0x6a00
	s_waitcnt lgkmcnt(6)
	v_mfma_f32_32x32x16_bf16 v[50:65], v[208:211], v[224:227], v[50:65]
	ds_read_b64_tr_b16 v[224:225], v183 offset:0x7200
	ds_read_b64_tr_b16 v[226:227], v183 offset:0x7a00
	s_waitcnt lgkmcnt(6)
	v_mfma_f32_32x32x16_bf16 v[34:49], v[204:207], v[212:215], v[34:49]
	ds_read_b64_tr_b16 v[212:213], v183 offset:0x4400
	ds_read_b64_tr_b16 v[214:215], v183 offset:0x4c00
	s_waitcnt lgkmcnt(6)
	v_mfma_f32_32x32x16_bf16 v[34:49], v[110:113], v[216:219], v[34:49]
	ds_read_b64_tr_b16 v[216:217], v183 offset:0x5400
	ds_read_b64_tr_b16 v[218:219], v183 offset:0x5c00
	s_waitcnt lgkmcnt(6)
	v_mfma_f32_32x32x16_bf16 v[34:49], v[98:101], v[220:223], v[34:49]
	ds_read_b64_tr_b16 v[220:221], v183 offset:0x6400
	ds_read_b64_tr_b16 v[222:223], v183 offset:0x6c00
	s_waitcnt lgkmcnt(6)
	v_mfma_f32_32x32x16_bf16 v[34:49], v[208:211], v[224:227], v[34:49]
	ds_read_b64_tr_b16 v[224:225], v183 offset:0x7400
	ds_read_b64_tr_b16 v[226:227], v183 offset:0x7c00
	s_waitcnt lgkmcnt(6)
	v_mfma_f32_32x32x16_bf16 v[18:33], v[204:207], v[212:215], v[18:33]
	ds_read_b64_tr_b16 v[212:213], v183 offset:0x4600
	ds_read_b64_tr_b16 v[214:215], v183 offset:0x4e00
	s_waitcnt lgkmcnt(6)
	v_mfma_f32_32x32x16_bf16 v[18:33], v[110:113], v[216:219], v[18:33]
	ds_read_b64_tr_b16 v[216:217], v183 offset:0x5600
	ds_read_b64_tr_b16 v[218:219], v183 offset:0x5e00
	s_waitcnt lgkmcnt(6)
	v_mfma_f32_32x32x16_bf16 v[18:33], v[98:101], v[220:223], v[18:33]
	ds_read_b64_tr_b16 v[220:221], v183 offset:0x6600
	ds_read_b64_tr_b16 v[222:223], v183 offset:0x6e00
	s_waitcnt lgkmcnt(6)
	v_mfma_f32_32x32x16_bf16 v[18:33], v[208:211], v[224:227], v[18:33]
	ds_read_b64_tr_b16 v[224:225], v183 offset:0x7600
	ds_read_b64_tr_b16 v[226:227], v183 offset:0x7e00
	s_waitcnt lgkmcnt(6)
	v_mfma_f32_32x32x16_bf16 v[2:17], v[204:207], v[212:215], v[2:17]
	s_waitcnt lgkmcnt(4)
	v_mfma_f32_32x32x16_bf16 v[2:17], v[110:113], v[216:219], v[2:17]
	s_waitcnt lgkmcnt(2)
	v_mfma_f32_32x32x16_bf16 v[2:17], v[98:101], v[220:223], v[2:17]
	s_waitcnt lgkmcnt(0)
	v_mfma_f32_32x32x16_bf16 v[2:17], v[208:211], v[224:227], v[2:17]
.Lmskip_fox_3:
	s_andn2_b64 vcc, exec, s[22:23]
	s_cbranch_vccnz .Lnok_fox
	s_waitcnt vmcnt(1)
	ds_write_b128 v193, v[154:157] offset:49152
	s_waitcnt vmcnt(0)
	ds_write_b128 v193, v[158:161] offset:57344
.Lnok_fox:
	s_sub_i32 s0, s11, s27
	s_cmp_ge_i32 s0, 31
	s_cbranch_scc1 .Lp1skip_fox_3
	ds_read_b128 v[100:103], v198 offset:256
	ds_read_b128 v[110:113], v198 offset:288
	ds_read_b128 v[202:205], v198 offset:384
	ds_read_b128 v[206:209], v198 offset:416
	ds_read_b128 v[210:213], v198 offset:320
	ds_read_b128 v[214:217], v198 offset:352
	ds_read_b128 v[218:221], v198 offset:448
	ds_read_b128 v[222:225], v198 offset:480
	s_waitcnt lgkmcnt(7)
	s_waitcnt lgkmcnt(6)
	v_xor_b32_e32 v107, 0x80000000, v113
	v_xor_b32_e32 v106, 0x80000000, v112
	s_waitcnt lgkmcnt(3)
	v_xor_b32_e32 v113, 0x80000000, v213
	v_xor_b32_e32 v112, 0x80000000, v212
	s_waitcnt lgkmcnt(2)
	v_xor_b32_e32 v213, 0x80000000, v217
	v_xor_b32_e32 v212, 0x80000000, v216
	v_fma_f32 v98, v86, s12, -v110
	v_fma_f32 v99, v87, s12, -v111
	v_fma_f32 v86, v96, s12, v212
	v_fma_f32 v87, v97, s12, v213
	v_fma_f32 v88, v88, s12, v106
	v_fma_f32 v89, v89, s12, v107
	v_fma_f32 v84, v84, s12, -v102
	v_fma_f32 v85, v85, s12, -v103
	v_fma_f32 v96, v82, s12, -v100
	v_fma_f32 v97, v83, s12, -v101
	s_waitcnt lgkmcnt(1)
	v_xor_b32_e32 v107, 0x80000000, v221
	v_xor_b32_e32 v106, 0x80000000, v220
	s_waitcnt lgkmcnt(0)
	v_xor_b32_e32 v111, 0x80000000, v225
	v_xor_b32_e32 v110, 0x80000000, v224
	s_add_i32 s0, s11, 64
	v_fma_f32 v94, v94, s12, -v214
	v_fma_f32 v95, v95, s12, -v215
	v_fma_f32 v90, v90, s12, -v210
	v_fma_f32 v91, v91, s12, -v211
	v_fma_f32 v92, v92, s12, v112
	v_fma_f32 v93, v93, s12, v113
	v_fma_f32 v82, v78, s12, -v222
	v_fma_f32 v83, v79, s12, -v223
	v_fma_f32 v74, v74, s12, -v218
	v_fma_f32 v75, v75, s12, -v219
	v_fma_f32 v78, v70, s12, -v206
	v_fma_f32 v79, v71, s12, -v207
	v_fma_f32 v70, v80, s12, v110
	v_fma_f32 v71, v81, s12, v111
	v_fma_f32 v76, v76, s12, v106
	v_fma_f32 v77, v77, s12, v107
	v_fma_f32 v100, v72, s12, -v208
	v_fma_f32 v101, v73, s12, -v209
	v_fma_f32 v102, v68, s12, -v204
	v_fma_f32 v103, v69, s12, -v205
	s_cmp_le_i32 s0, s27
	v_fma_f32 v80, v66, s12, -v202
	v_fma_f32 v81, v67, s12, -v203
	s_cbranch_scc1 .LBB0_655
	v_cmp_gt_i32_e64 s[92:93], 26, v199
	v_cmp_gt_i32_e64 s[94:95], 27, v199
	v_cmp_gt_i32_e64 s[90:91], 25, v199
	s_and_b64 s[92:93], s[94:95], s[92:93]
	v_cmp_gt_i32_e64 s[88:89], 24, v199
	s_and_b64 s[90:91], s[92:93], s[90:91]
	v_cmp_gt_i32_e64 s[86:87], 19, v199
	s_and_b64 s[88:89], s[90:91], s[88:89]
	v_cmp_gt_i32_e64 s[84:85], 18, v199
	s_and_b64 s[86:87], s[88:89], s[86:87]
	v_cmp_gt_i32_e64 s[82:83], 17, v199
	s_and_b64 s[84:85], s[86:87], s[84:85]
	v_cmp_gt_i32_e64 s[80:81], 16, v199
	s_and_b64 s[82:83], s[84:85], s[82:83]
	v_cmp_gt_i32_e64 s[78:79], 11, v199
	s_and_b64 s[80:81], s[82:83], s[80:81]
	v_cmp_gt_i32_e64 s[76:77], 10, v199
	s_and_b64 s[78:79], s[80:81], s[78:79]
	v_cmp_gt_i32_e64 s[74:75], 9, v199
	s_and_b64 s[76:77], s[78:79], s[76:77]
	v_cmp_gt_i32_e64 s[72:73], 8, v199
	s_and_b64 s[74:75], s[76:77], s[74:75]
	v_cmp_gt_i32_e64 s[70:71], 3, v199
	s_and_b64 s[72:73], s[74:75], s[72:73]
	v_cmp_gt_i32_e64 s[68:69], 2, v199
	s_and_b64 s[70:71], s[72:73], s[70:71]
	v_cmp_gt_i32_e64 s[2:3], 1, v199
	s_and_b64 s[68:69], s[70:71], s[68:69]
	v_cmp_gt_i32_e64 s[0:1], 0, v199
	s_and_b64 s[2:3], s[68:69], s[2:3]
	s_and_b64 s[0:1], s[2:3], s[0:1]
	v_cmp_gt_i32_e64 s[66:67], 58, v199
	v_cndmask_b32_e64 v96, v96, v175, s[0:1]
	v_cmp_gt_i32_e64 s[0:1], 59, v199
	v_cmp_gt_i32_e64 s[64:65], 57, v199
	v_cmp_gt_i32_e64 s[62:63], 56, v199
	v_cndmask_b32_e64 v71, v71, v175, s[0:1]
	s_and_b64 s[0:1], s[0:1], s[66:67]
	v_cndmask_b32_e64 v70, v70, v175, s[0:1]
	s_and_b64 s[0:1], s[0:1], s[64:65]
	v_cmp_gt_i32_e64 s[60:61], 51, v199
	v_cndmask_b32_e64 v83, v83, v175, s[0:1]
	s_and_b64 s[0:1], s[0:1], s[62:63]
	v_cmp_gt_i32_e64 s[58:59], 50, v199
	v_cndmask_b32_e64 v82, v82, v175, s[0:1]
	s_and_b64 s[0:1], s[0:1], s[60:61]
	v_cmp_gt_i32_e64 s[56:57], 49, v199
	v_cndmask_b32_e64 v77, v77, v175, s[0:1]
	s_and_b64 s[0:1], s[0:1], s[58:59]
	v_cmp_gt_i32_e64 s[54:55], 48, v199
	v_cndmask_b32_e64 v76, v76, v175, s[0:1]
	s_and_b64 s[0:1], s[0:1], s[56:57]
	v_cmp_gt_i32_e64 s[52:53], 43, v199
	v_cndmask_b32_e64 v75, v75, v175, s[0:1]
	s_and_b64 s[0:1], s[0:1], s[54:55]
	v_cmp_gt_i32_e64 s[50:51], 42, v199
	v_cndmask_b32_e64 v74, v74, v175, s[0:1]
	s_and_b64 s[0:1], s[0:1], s[52:53]
	v_cmp_gt_i32_e64 s[48:49], 41, v199
	v_cndmask_b32_e64 v101, v101, v175, s[0:1]
	s_and_b64 s[0:1], s[0:1], s[50:51]
	v_cmp_gt_i32_e64 s[46:47], 40, v199
	v_cndmask_b32_e64 v100, v100, v175, s[0:1]
	s_and_b64 s[0:1], s[0:1], s[48:49]
	v_cmp_gt_i32_e64 s[44:45], 35, v199
	v_cndmask_b32_e64 v79, v79, v175, s[0:1]
	s_and_b64 s[0:1], s[0:1], s[46:47]
	v_cmp_gt_i32_e64 s[42:43], 34, v199
	v_cndmask_b32_e64 v78, v78, v175, s[0:1]
	s_and_b64 s[0:1], s[0:1], s[44:45]
	v_cmp_gt_i32_e64 s[40:41], 33, v199
	v_cndmask_b32_e64 v103, v103, v175, s[0:1]
	s_and_b64 s[0:1], s[0:1], s[42:43]
	v_cmp_gt_i32_e32 vcc, 32, v199
	v_cndmask_b32_e64 v102, v102, v175, s[0:1]
	s_and_b64 s[0:1], s[0:1], s[40:41]
	v_cndmask_b32_e64 v94, v94, v175, s[88:89]
	v_readlane_b32 s88, v242, 2
	s_and_b64 vcc, s[0:1], vcc
	v_cndmask_b32_e64 v87, v87, v175, s[94:95]
	v_cndmask_b32_e64 v86, v86, v175, s[92:93]
	s_movk_i32 s93, 0x6018
	s_mov_b32 s92, 0xf800000
	v_cndmask_b32_e64 v95, v95, v175, s[90:91]
	s_mov_b64 s[90:91], s[16:17]
	v_readlane_b32 s89, v242, 3
	v_cndmask_b32_e64 v93, v93, v175, s[86:87]
	v_readlane_b32 s86, v242, 0
	v_cndmask_b32_e64 v92, v92, v175, s[84:85]
	v_cndmask_b32_e64 v91, v91, v175, s[82:83]
	s_movk_i32 s83, 0x6000
	v_cndmask_b32_e64 v90, v90, v175, s[80:81]
	v_cndmask_b32_e64 v89, v89, v175, s[78:79]
	v_cndmask_b32_e64 v88, v88, v175, s[76:77]
	v_cndmask_b32_e64 v99, v99, v175, s[74:75]
	v_cndmask_b32_e64 v98, v98, v175, s[72:73]
	v_cndmask_b32_e64 v85, v85, v175, s[70:71]
	v_cndmask_b32_e64 v84, v84, v175, s[68:69]
	v_cndmask_b32_e64 v97, v97, v175, s[2:3]
	s_mov_b32 s56, s30
	v_cndmask_b32_e64 v81, v81, v175, s[0:1]
	v_cndmask_b32_e32 v80, v80, v175, vcc
	v_readlane_b32 s87, v242, 1

.Lp1join_fox_3:
	s_andn2_b64 vcc, exec, s[22:23]
	s_waitcnt lgkmcnt(0)
	s_barrier
	s_cbranch_vccnz .LBB0_657
	ds_write_b128 v194, v[146:149] offset:16384
	ds_write_b128 v195, v[150:153] offset:16384

.Lmskip_dif_1:
	s_waitcnt vmcnt(2)
	ds_write_b128 v164, v[122:125] offset:32768
	s_waitcnt vmcnt(0)
	ds_write_b128 v164, v[126:129] offset:40960
	s_sub_i32 s0, s9, s25
	s_cmp_ge_i32 s0, 95
	s_cbranch_scc1 .Lp1skip_dif_1
	s_cmp_le_i32 s9, s25
	s_cbranch_scc1 .LBB0_825
	v_add_u32_e32 v132, 64, v169
	v_cmp_gt_i32_e64 s[92:93], 26, v132
	v_cmp_gt_i32_e64 s[94:95], 27, v132
	v_cmp_gt_i32_e64 s[90:91], 25, v132
	s_and_b64 s[92:93], s[94:95], s[92:93]
	v_cmp_gt_i32_e64 s[88:89], 24, v132
	s_and_b64 s[90:91], s[92:93], s[90:91]
	v_cmp_gt_i32_e64 s[86:87], 19, v132
	s_and_b64 s[88:89], s[90:91], s[88:89]
	v_cmp_gt_i32_e64 s[84:85], 18, v132
	s_and_b64 s[86:87], s[88:89], s[86:87]
	v_cmp_gt_i32_e64 s[82:83], 17, v132
	s_and_b64 s[84:85], s[86:87], s[84:85]
	v_cmp_gt_i32_e64 s[80:81], 16, v132
	s_and_b64 s[82:83], s[84:85], s[82:83]
	v_cmp_gt_i32_e64 s[78:79], 11, v132
	s_and_b64 s[80:81], s[82:83], s[80:81]
	v_cmp_gt_i32_e64 s[76:77], 10, v132
	s_and_b64 s[78:79], s[80:81], s[78:79]
	v_cmp_gt_i32_e64 s[74:75], 9, v132
	s_and_b64 s[76:77], s[78:79], s[76:77]
	v_cmp_gt_i32_e64 s[72:73], 8, v132
	s_and_b64 s[74:75], s[76:77], s[74:75]
	v_cmp_gt_i32_e64 s[70:71], 3, v132
	s_and_b64 s[72:73], s[74:75], s[72:73]
	v_cmp_gt_i32_e64 s[68:69], 2, v132
	s_and_b64 s[70:71], s[72:73], s[70:71]
	v_cmp_gt_i32_e64 s[2:3], 1, v132
	s_and_b64 s[68:69], s[70:71], s[68:69]
	v_cmp_gt_i32_e64 s[0:1], 0, v132
	s_and_b64 s[2:3], s[68:69], s[2:3]
	s_and_b64 s[0:1], s[2:3], s[0:1]
	v_cmp_gt_i32_e64 s[66:67], 58, v132
	v_cndmask_b32_e64 v82, v82, v175, s[0:1]
	v_cmp_gt_i32_e64 s[0:1], 59, v132
	v_cmp_gt_i32_e64 s[64:65], 57, v132
	v_cmp_gt_i32_e64 s[62:63], 56, v132
	v_cndmask_b32_e64 v81, v81, v175, s[0:1]
	s_and_b64 s[0:1], s[0:1], s[66:67]
	v_cndmask_b32_e64 v80, v80, v175, s[0:1]
	s_and_b64 s[0:1], s[0:1], s[64:65]
	v_cmp_gt_i32_e64 s[60:61], 51, v132
	v_cndmask_b32_e64 v79, v79, v175, s[0:1]
	s_and_b64 s[0:1], s[0:1], s[62:63]
	v_cmp_gt_i32_e64 s[58:59], 50, v132
	v_cndmask_b32_e64 v78, v78, v175, s[0:1]
	s_and_b64 s[0:1], s[0:1], s[60:61]
	v_cmp_gt_i32_e64 s[56:57], 49, v132
	v_cndmask_b32_e64 v77, v77, v175, s[0:1]
	s_and_b64 s[0:1], s[0:1], s[58:59]
	v_cmp_gt_i32_e64 s[54:55], 48, v132
	v_cndmask_b32_e64 v76, v76, v175, s[0:1]
	s_and_b64 s[0:1], s[0:1], s[56:57]
	v_cmp_gt_i32_e64 s[52:53], 43, v132
	v_cndmask_b32_e64 v75, v75, v175, s[0:1]
	s_and_b64 s[0:1], s[0:1], s[54:55]
	v_cmp_gt_i32_e64 s[50:51], 42, v132
	v_cndmask_b32_e64 v74, v74, v175, s[0:1]
	s_and_b64 s[0:1], s[0:1], s[52:53]
	v_cmp_gt_i32_e64 s[48:49], 41, v132
	v_cndmask_b32_e64 v73, v73, v175, s[0:1]
	s_and_b64 s[0:1], s[0:1], s[50:51]
	v_cmp_gt_i32_e64 s[46:47], 40, v132
	v_cndmask_b32_e64 v72, v72, v175, s[0:1]
	s_and_b64 s[0:1], s[0:1], s[48:49]
	v_cmp_gt_i32_e64 s[44:45], 35, v132
	v_cndmask_b32_e64 v71, v71, v175, s[0:1]
	s_and_b64 s[0:1], s[0:1], s[46:47]
	v_cmp_gt_i32_e64 s[42:43], 34, v132
	v_cndmask_b32_e64 v70, v70, v175, s[0:1]
	s_and_b64 s[0:1], s[0:1], s[44:45]
	v_cmp_gt_i32_e64 s[40:41], 33, v132
	v_cndmask_b32_e64 v69, v69, v175, s[0:1]
	s_and_b64 s[0:1], s[0:1], s[42:43]
	v_cmp_gt_i32_e32 vcc, 32, v132
	v_cndmask_b32_e64 v68, v68, v175, s[0:1]
	s_and_b64 s[0:1], s[0:1], s[40:41]
	s_and_b64 vcc, s[0:1], vcc
	v_cndmask_b32_e64 v97, v97, v175, s[94:95]
	v_cndmask_b32_e64 v96, v96, v175, s[92:93]
	v_cndmask_b32_e64 v95, v95, v175, s[90:91]
	v_cndmask_b32_e64 v94, v94, v175, s[88:89]
	v_cndmask_b32_e64 v93, v93, v175, s[86:87]
	v_cndmask_b32_e64 v92, v92, v175, s[84:85]
	v_cndmask_b32_e64 v91, v91, v175, s[82:83]
	v_cndmask_b32_e64 v90, v90, v175, s[80:81]
	v_cndmask_b32_e64 v89, v89, v175, s[78:79]
	v_cndmask_b32_e64 v88, v88, v175, s[76:77]
	v_cndmask_b32_e64 v87, v87, v175, s[74:75]
	v_cndmask_b32_e64 v86, v86, v175, s[72:73]
	v_cndmask_b32_e64 v85, v85, v175, s[70:71]
	v_cndmask_b32_e64 v84, v84, v175, s[68:69]
	v_cndmask_b32_e64 v83, v83, v175, s[2:3]
	v_cndmask_b32_e64 v67, v67, v175, s[0:1]
	v_cndmask_b32_e32 v66, v66, v175, vcc

.Lp1join_dif_1:
	v_cmp_gt_f32_e32 vcc, 1.0, v181
	s_waitcnt lgkmcnt(0)
	s_barrier
	ds_write_b128 v165, v[114:117]
	ds_write_b128 v166, v[118:121]
	s_cbranch_vccz .LBB0_829
	s_and_saveexec_b64 s[0:1], s[38:39]
	ds_write_b32 v155, v181 offset:128
	s_or_b64 exec, exec, s[0:1]
	s_waitcnt lgkmcnt(0)
	ds_read_b128 v[134:137], v154 offset:224
	ds_read_b128 v[138:141], v154 offset:192
	ds_read_b128 v[142:145], v154 offset:160
	ds_read_b128 v[184:187], v154 offset:128
	s_waitcnt lgkmcnt(3)
	v_mul_f32 v64, v64, v136
	v_mul_f32 v65, v65, v137
	s_waitcnt lgkmcnt(2)
	v_mul_f32 v60, v60, v140
	v_mul_f32 v61, v61, v141
	s_waitcnt lgkmcnt(1)
	v_mul_f32 v56, v56, v144
	v_mul_f32 v57, v57, v145
	s_waitcnt lgkmcnt(0)
	v_mul_f32 v52, v52, v186
	v_mul_f32 v53, v53, v187
	v_mul_f32 v62, v62, v134
	v_mul_f32 v63, v63, v135
	v_mul_f32 v58, v58, v138
	v_mul_f32 v59, v59, v139
	v_mul_f32 v54, v54, v142
	v_mul_f32 v55, v55, v143
	v_mul_f32 v50, v50, v184
	v_mul_f32 v51, v51, v185
	v_mul_f32 v48, v48, v136
	v_mul_f32 v49, v49, v137
	v_mul_f32 v44, v44, v140
	v_mul_f32 v45, v45, v141
	v_mul_f32 v40, v40, v144
	v_mul_f32 v41, v41, v145
	v_mul_f32 v36, v36, v186
	v_mul_f32 v37, v37, v187
	v_mul_f32 v46, v46, v134
	v_mul_f32 v47, v47, v135
	v_mul_f32 v42, v42, v138
	v_mul_f32 v43, v43, v139
	v_mul_f32 v38, v38, v142
	v_mul_f32 v39, v39, v143
	v_mul_f32 v34, v34, v184
	v_mul_f32 v35, v35, v185
	v_mul_f32 v32, v32, v136
	v_mul_f32 v33, v33, v137
	v_mul_f32 v28, v28, v140
	v_mul_f32 v29, v29, v141
	v_mul_f32 v24, v24, v144
	v_mul_f32 v25, v25, v145
	v_mul_f32 v20, v20, v186
	v_mul_f32 v21, v21, v187
	v_mul_f32 v30, v30, v134
	v_mul_f32 v31, v31, v135
	v_mul_f32 v26, v26, v138
	v_mul_f32 v27, v27, v139
	v_mul_f32 v22, v22, v142
	v_mul_f32 v23, v23, v143
	v_mul_f32 v18, v18, v184
	v_mul_f32 v19, v19, v185
	v_mul_f32 v16, v16, v136
	v_mul_f32 v17, v17, v137
	v_mul_f32 v12, v12, v140
	v_mul_f32 v13, v13, v141
	v_mul_f32 v8, v8, v144
	v_mul_f32 v9, v9, v145
	v_mul_f32 v4, v4, v186
	v_mul_f32 v5, v5, v187
	v_mul_f32 v14, v14, v134
	v_mul_f32 v15, v15, v135
	v_mul_f32 v10, v10, v138
	v_mul_f32 v11, v11, v139
	v_mul_f32 v6, v6, v142
	v_mul_f32 v7, v7, v143
	v_mul_f32 v2, v2, v184
	v_mul_f32 v3, v3, v185

.Lmskip_dif_2:
	s_waitcnt lgkmcnt(0)
	s_sub_i32 s0, s9, s25
	s_cmp_ge_i32 s0, 95
	s_cbranch_scc1 .Lfskip_dif_3
	v_add_f32_e32 v182, 0, v146
	v_add_f32_e32 v182, v168, v182
	v_add_f32_e32 v182, v144, v182
	v_add_f32_e32 v182, v147, v182
	v_add_f32_e32 v182, v142, v182
	v_add_f32_e32 v182, v145, v182
	v_add_f32_e32 v182, v141, v182
	v_add_f32_e32 v182, v143, v182
	v_add_f32_e32 v182, v138, v182
	v_add_f32_e32 v182, v140, v182
	v_add_f32_e32 v182, v136, v182
	v_add_f32_e32 v182, v139, v182
	v_exp_f32_e32 v199, v184
	v_add_f32_e32 v182, v134, v182
	v_exp_f32_e32 v200, v185
	v_add_f32_e32 v182, v137, v182
	v_exp_f32_e32 v201, v186
	v_add_f32_e32 v182, v133, v182
	v_exp_f32_e32 v202, v187
	v_add_f32_e32 v182, v135, v182
	v_exp_f32_e32 v188, v188
	v_add_f32_e32 v182, v199, v182
	v_exp_f32_e32 v189, v189
	v_add_f32_e32 v182, v200, v182
	v_exp_f32_e32 v190, v190
	v_add_f32_e32 v182, v201, v182
	v_exp_f32_e32 v191, v191
	v_add_f32_e32 v182, v202, v182
	v_exp_f32_e32 v192, v192
	v_add_f32_e32 v182, v188, v182
	v_exp_f32_e32 v193, v193
	v_add_f32_e32 v182, v189, v182
	v_exp_f32_e32 v194, v194
	v_add_f32_e32 v182, v190, v182
	v_exp_f32_e32 v195, v195
	v_add_f32_e32 v182, v191, v182
	v_exp_f32_e32 v196, v196
	v_add_f32_e32 v182, v192, v182
	v_exp_f32_e32 v197, v197
	v_add_f32_e32 v182, v193, v182
	v_exp_f32_e32 v198, v198
	v_add_f32_e32 v182, v194, v182
	v_exp_f32_e32 v203, v183
	v_add_f32_e32 v182, v195, v182
	v_add_f32_e32 v182, v196, v182
	v_add_f32_e32 v182, v197, v182
	v_add_f32_e32 v182, v198, v182
	v_add_f32_e32 v182, v203, v182
	v_mov_b32_e32 v183, v182
	s_nop 1
	v_permlane32_swap_b32_e32 v182, v183
	v_cvt_pk_bf16_f32 v184, v146, v168
	v_cvt_pk_bf16_f32 v185, v144, v147
	v_cvt_pk_bf16_f32 v186, v142, v145
	v_cvt_pk_bf16_f32 v187, v141, v143
	v_cvt_pk_bf16_f32 v138, v138, v140
	v_cvt_pk_bf16_f32 v139, v136, v139
	v_cvt_pk_bf16_f32 v140, v134, v137
	v_cvt_pk_bf16_f32 v141, v133, v135
	v_cvt_pk_bf16_f32 v134, v199, v200
	v_cvt_pk_bf16_f32 v135, v201, v202
	v_cvt_pk_bf16_f32 v136, v188, v189
	v_cvt_pk_bf16_f32 v137, v190, v191
	v_cvt_pk_bf16_f32 v142, v192, v193
	v_cvt_pk_bf16_f32 v143, v194, v195
	v_cvt_pk_bf16_f32 v144, v196, v197
	v_cvt_pk_bf16_f32 v145, v198, v203
	s_nop 0
	v_permlane32_swap_b32_e32 v184, v186
	v_permlane32_swap_b32_e32 v185, v187
	v_permlane32_swap_b32_e32 v138, v140
	v_permlane32_swap_b32_e32 v139, v141
	v_permlane32_swap_b32_e32 v134, v136
	v_permlane32_swap_b32_e32 v135, v137
	v_permlane32_swap_b32_e32 v142, v144
	v_permlane32_swap_b32_e32 v143, v145
	ds_read_b64_tr_b16 v[188:189], v153 offset:0x4000
	ds_read_b64_tr_b16 v[190:191], v153 offset:0x4800
	ds_read_b64_tr_b16 v[192:193], v153 offset:0x5000
	ds_read_b64_tr_b16 v[194:195], v153 offset:0x5800
	ds_read_b64_tr_b16 v[196:197], v153 offset:0x6000
	ds_read_b64_tr_b16 v[198:199], v153 offset:0x6800
	ds_read_b64_tr_b16 v[200:201], v153 offset:0x7000
	ds_read_b64_tr_b16 v[202:203], v153 offset:0x7800
	s_nop 0
	s_waitcnt lgkmcnt(6)
	v_mfma_f32_32x32x16_bf16 v[50:65], v[184:187], v[188:191], v[50:65]
	ds_read_b64_tr_b16 v[188:189], v153 offset:0x4200
	ds_read_b64_tr_b16 v[190:191], v153 offset:0x4a00
	s_waitcnt lgkmcnt(6)
	v_mfma_f32_32x32x16_bf16 v[50:65], v[138:141], v[192:195], v[50:65]
	ds_read_b64_tr_b16 v[192:193], v153 offset:0x5200
	ds_read_b64_tr_b16 v[194:195], v153 offset:0x5a00
	s_waitcnt lgkmcnt(6)
	v_mfma_f32_32x32x16_bf16 v[50:65], v[134:137], v[196:199], v[50:65]
	ds_read_b64_tr_b16 v[196:197], v153 offset:0x6200
	ds_read_b64_tr_b16 v[198:199], v153 offset:0x6a00
	s_waitcnt lgkmcnt(6)
	v_mfma_f32_32x32x16_bf16 v[50:65], v[142:145], v[200:203], v[50:65]
	ds_read_b64_tr_b16 v[200:201], v153 offset:0x7200
	ds_read_b64_tr_b16 v[202:203], v153 offset:0x7a00
	s_waitcnt lgkmcnt(6)
	v_mfma_f32_32x32x16_bf16 v[34:49], v[184:187], v[188:191], v[34:49]
	ds_read_b64_tr_b16 v[188:189], v153 offset:0x4400
	ds_read_b64_tr_b16 v[190:191], v153 offset:0x4c00
	s_waitcnt lgkmcnt(6)
	v_mfma_f32_32x32x16_bf16 v[34:49], v[138:141], v[192:195], v[34:49]
	ds_read_b64_tr_b16 v[192:193], v153 offset:0x5400
	ds_read_b64_tr_b16 v[194:195], v153 offset:0x5c00
	s_waitcnt lgkmcnt(6)
	v_mfma_f32_32x32x16_bf16 v[34:49], v[134:137], v[196:199], v[34:49]
	ds_read_b64_tr_b16 v[196:197], v153 offset:0x6400
	ds_read_b64_tr_b16 v[198:199], v153 offset:0x6c00
	s_waitcnt lgkmcnt(6)
	v_mfma_f32_32x32x16_bf16 v[34:49], v[142:145], v[200:203], v[34:49]
	ds_read_b64_tr_b16 v[200:201], v153 offset:0x7400
	ds_read_b64_tr_b16 v[202:203], v153 offset:0x7c00
	s_waitcnt lgkmcnt(6)
	v_mfma_f32_32x32x16_bf16 v[18:33], v[184:187], v[188:191], v[18:33]
	ds_read_b64_tr_b16 v[188:189], v153 offset:0x4600
	ds_read_b64_tr_b16 v[190:191], v153 offset:0x4e00
	s_waitcnt lgkmcnt(6)
	v_mfma_f32_32x32x16_bf16 v[18:33], v[138:141], v[192:195], v[18:33]
	ds_read_b64_tr_b16 v[192:193], v153 offset:0x5600
	ds_read_b64_tr_b16 v[194:195], v153 offset:0x5e00
	s_waitcnt lgkmcnt(6)
	v_mfma_f32_32x32x16_bf16 v[18:33], v[134:137], v[196:199], v[18:33]
	ds_read_b64_tr_b16 v[196:197], v153 offset:0x6600
	ds_read_b64_tr_b16 v[198:199], v153 offset:0x6e00
	s_waitcnt lgkmcnt(6)
	v_mfma_f32_32x32x16_bf16 v[18:33], v[142:145], v[200:203], v[18:33]
	ds_read_b64_tr_b16 v[200:201], v153 offset:0x7600
	ds_read_b64_tr_b16 v[202:203], v153 offset:0x7e00
	s_waitcnt lgkmcnt(6)
	v_mfma_f32_32x32x16_bf16 v[2:17], v[184:187], v[188:191], v[2:17]
	s_waitcnt lgkmcnt(4)
	v_mfma_f32_32x32x16_bf16 v[2:17], v[138:141], v[192:195], v[2:17]
	s_waitcnt lgkmcnt(2)
	v_mfma_f32_32x32x16_bf16 v[2:17], v[134:137], v[196:199], v[2:17]
	s_waitcnt lgkmcnt(0)
	v_mfma_f32_32x32x16_bf16 v[2:17], v[142:145], v[200:203], v[2:17]
.Lmskip_dif_3:
	s_andn2_b64 vcc, exec, s[22:23]
	s_cbranch_vccnz .Lnok_dif
	s_waitcnt vmcnt(2)
	ds_write_b128 v164, v[122:125] offset:49152
	s_waitcnt vmcnt(0)
	ds_write_b128 v164, v[126:129] offset:57344
.Lnok_dif:
	s_sub_i32 s0, s9, s25
	s_cmp_ge_i32 s0, 31
	s_cbranch_scc1 .Lp1skip_dif_3
	s_add_i32 s0, s9, 64
	s_cmp_le_i32 s0, s25
	s_cbranch_scc1 .LBB0_833
	v_cmp_gt_i32_e64 s[92:93], 26, v169
	v_cmp_gt_i32_e64 s[94:95], 27, v169
	v_cmp_gt_i32_e64 s[90:91], 25, v169
	s_and_b64 s[92:93], s[94:95], s[92:93]
	v_cmp_gt_i32_e64 s[88:89], 24, v169
	s_and_b64 s[90:91], s[92:93], s[90:91]
	v_cmp_gt_i32_e64 s[86:87], 19, v169
	s_and_b64 s[88:89], s[90:91], s[88:89]
	v_cmp_gt_i32_e64 s[84:85], 18, v169
	s_and_b64 s[86:87], s[88:89], s[86:87]
	v_cmp_gt_i32_e64 s[82:83], 17, v169
	s_and_b64 s[84:85], s[86:87], s[84:85]
	v_cmp_gt_i32_e64 s[80:81], 16, v169
	s_and_b64 s[82:83], s[84:85], s[82:83]
	v_cmp_gt_i32_e64 s[78:79], 11, v169
	s_and_b64 s[80:81], s[82:83], s[80:81]
	v_cmp_gt_i32_e64 s[76:77], 10, v169
	s_and_b64 s[78:79], s[80:81], s[78:79]
	v_cmp_gt_i32_e64 s[74:75], 9, v169
	s_and_b64 s[76:77], s[78:79], s[76:77]
	v_cmp_gt_i32_e64 s[72:73], 8, v169
	s_and_b64 s[74:75], s[76:77], s[74:75]
	v_cmp_gt_i32_e64 s[70:71], 3, v169
	s_and_b64 s[72:73], s[74:75], s[72:73]
	v_cmp_gt_i32_e64 s[68:69], 2, v169
	s_and_b64 s[70:71], s[72:73], s[70:71]
	v_cmp_gt_i32_e64 s[2:3], 1, v169
	s_and_b64 s[68:69], s[70:71], s[68:69]
	v_cmp_gt_i32_e64 s[0:1], 0, v169
	s_and_b64 s[2:3], s[68:69], s[2:3]
	s_and_b64 s[0:1], s[2:3], s[0:1]
	v_cmp_gt_i32_e64 s[66:67], 58, v169
	v_cndmask_b32_e64 v82, v82, v175, s[0:1]
	v_cmp_gt_i32_e64 s[0:1], 59, v169
	v_cmp_gt_i32_e64 s[64:65], 57, v169
	v_cmp_gt_i32_e64 s[62:63], 56, v169
	v_cndmask_b32_e64 v81, v81, v175, s[0:1]
	s_and_b64 s[0:1], s[0:1], s[66:67]
	v_cndmask_b32_e64 v80, v80, v175, s[0:1]
	s_and_b64 s[0:1], s[0:1], s[64:65]
	v_cmp_gt_i32_e64 s[60:61], 51, v169
	v_cndmask_b32_e64 v79, v79, v175, s[0:1]
	s_and_b64 s[0:1], s[0:1], s[62:63]
	v_cmp_gt_i32_e64 s[58:59], 50, v169
	v_cndmask_b32_e64 v78, v78, v175, s[0:1]
	s_and_b64 s[0:1], s[0:1], s[60:61]
	v_cmp_gt_i32_e64 s[56:57], 49, v169
	v_cndmask_b32_e64 v77, v77, v175, s[0:1]
	s_and_b64 s[0:1], s[0:1], s[58:59]
	v_cmp_gt_i32_e64 s[54:55], 48, v169
	v_cndmask_b32_e64 v76, v76, v175, s[0:1]
	s_and_b64 s[0:1], s[0:1], s[56:57]
	v_cmp_gt_i32_e64 s[52:53], 43, v169
	v_cndmask_b32_e64 v75, v75, v175, s[0:1]
	s_and_b64 s[0:1], s[0:1], s[54:55]
	v_cmp_gt_i32_e64 s[50:51], 42, v169
	v_cndmask_b32_e64 v74, v74, v175, s[0:1]
	s_and_b64 s[0:1], s[0:1], s[52:53]
	v_cmp_gt_i32_e64 s[48:49], 41, v169
	v_cndmask_b32_e64 v73, v73, v175, s[0:1]
	s_and_b64 s[0:1], s[0:1], s[50:51]
	v_cmp_gt_i32_e64 s[46:47], 40, v169
	v_cndmask_b32_e64 v72, v72, v175, s[0:1]
	s_and_b64 s[0:1], s[0:1], s[48:49]
	v_cmp_gt_i32_e64 s[44:45], 35, v169
	v_cndmask_b32_e64 v71, v71, v175, s[0:1]
	s_and_b64 s[0:1], s[0:1], s[46:47]
	v_cmp_gt_i32_e64 s[42:43], 34, v169
	v_cndmask_b32_e64 v70, v70, v175, s[0:1]
	s_and_b64 s[0:1], s[0:1], s[44:45]
	v_cmp_gt_i32_e64 s[40:41], 33, v169
	v_cndmask_b32_e64 v69, v69, v175, s[0:1]
	s_and_b64 s[0:1], s[0:1], s[42:43]
	v_cmp_gt_i32_e32 vcc, 32, v169
	v_cndmask_b32_e64 v68, v68, v175, s[0:1]
	s_and_b64 s[0:1], s[0:1], s[40:41]
	s_and_b64 vcc, s[0:1], vcc
	v_cndmask_b32_e64 v97, v97, v175, s[94:95]
	v_cndmask_b32_e64 v96, v96, v175, s[92:93]
	v_cndmask_b32_e64 v95, v95, v175, s[90:91]
	v_cndmask_b32_e64 v94, v94, v175, s[88:89]
	v_cndmask_b32_e64 v93, v93, v175, s[86:87]
	v_cndmask_b32_e64 v92, v92, v175, s[84:85]
	v_cndmask_b32_e64 v91, v91, v175, s[82:83]
	v_cndmask_b32_e64 v90, v90, v175, s[80:81]
	v_cndmask_b32_e64 v89, v89, v175, s[78:79]
	v_cndmask_b32_e64 v88, v88, v175, s[76:77]
	v_cndmask_b32_e64 v87, v87, v175, s[74:75]
	v_cndmask_b32_e64 v86, v86, v175, s[72:73]
	v_cndmask_b32_e64 v85, v85, v175, s[70:71]
	v_cndmask_b32_e64 v84, v84, v175, s[68:69]
	v_cndmask_b32_e64 v83, v83, v175, s[2:3]
	v_cndmask_b32_e64 v67, v67, v175, s[0:1]
	v_cndmask_b32_e32 v66, v66, v175, vcc

.Lp1join_dif_3:
	s_andn2_b64 vcc, exec, s[22:23]
	s_waitcnt lgkmcnt(0)
	s_barrier
	s_cbranch_vccnz .LBB0_835
	ds_write_b128 v165, v[114:117] offset:16384
	ds_write_b128 v166, v[118:121] offset:16384
